# grid barrier: the 16 per-XCD counter loads of the first-use completion scan issued back to back with one wait (was a load-wait ladder)
# speedup vs baseline: 1.0208x; 1.0208x over previous
.LBB0_156:
	v_readlane_b32 s6, v251, 29
	v_readlane_b32 s7, v251, 30
	v_readlane_b32 s1, v252, 29
	s_mov_b64 s[8:9], -1
	s_waitcnt lgkmcnt(0)
	s_nop 1
	global_load_dword v0, v131, s[6:7] sc1
	v_readlane_b32 s6, v251, 31
	v_readlane_b32 s7, v251, 32
	s_nop 4
	global_load_dword v1, v131, s[6:7] sc1
	v_readlane_b32 s6, v251, 33
	v_readlane_b32 s7, v251, 34
	s_nop 4
	global_load_dword v2, v131, s[6:7] sc1
	v_readlane_b32 s6, v251, 35
	v_readlane_b32 s7, v251, 36
	s_nop 4
	global_load_dword v3, v131, s[6:7] sc1
	v_readlane_b32 s6, v251, 37
	v_readlane_b32 s7, v251, 38
	s_nop 4
	global_load_dword v4, v131, s[6:7] sc1
	v_readlane_b32 s6, v251, 39
	v_readlane_b32 s7, v251, 40
	s_nop 4
	global_load_dword v5, v131, s[6:7] sc1
	v_readlane_b32 s6, v251, 41
	v_readlane_b32 s7, v251, 42
	s_nop 4
	global_load_dword v6, v131, s[6:7] sc1
	v_readlane_b32 s6, v251, 43
	v_readlane_b32 s7, v251, 44
	s_nop 4
	global_load_dword v7, v131, s[6:7] sc1
	v_readlane_b32 s6, v251, 45
	v_readlane_b32 s7, v251, 46
	s_nop 4
	global_load_dword v8, v131, s[6:7] sc1
	v_readlane_b32 s6, v251, 47
	v_readlane_b32 s7, v251, 48
	s_nop 4
	global_load_dword v9, v131, s[6:7] sc1
	v_readlane_b32 s6, v251, 49
	v_readlane_b32 s7, v251, 50
	s_nop 4
	global_load_dword v10, v131, s[6:7] sc1
	v_readlane_b32 s6, v251, 51
	v_readlane_b32 s7, v251, 52
	s_nop 4
	global_load_dword v11, v131, s[6:7] sc1
	v_readlane_b32 s6, v251, 53
	v_readlane_b32 s7, v251, 54
	s_nop 4
	global_load_dword v12, v131, s[6:7] sc1
	v_readlane_b32 s6, v251, 55
	v_readlane_b32 s7, v251, 56
	s_nop 4
	global_load_dword v13, v131, s[6:7] sc1
	v_readlane_b32 s6, v251, 57
	v_readlane_b32 s7, v251, 58
	s_nop 4
	global_load_dword v14, v131, s[6:7] sc1
	v_readlane_b32 s6, v251, 59
	v_readlane_b32 s7, v251, 60
	s_nop 4
	global_load_dword v15, v131, s[6:7] sc1
	s_mov_b64 s[6:7], -1
	s_waitcnt vmcnt(0)
	v_add_u32_e32 v16, v1, v0
	v_add_u32_e32 v16, v16, v2
	v_add_u32_e32 v16, v16, v3
	v_add_u32_e32 v16, v16, v4
	v_add_u32_e32 v16, v16, v5
	v_add_u32_e32 v16, v16, v6
	v_add_u32_e32 v16, v16, v7
	v_add_u32_e32 v16, v16, v8
	v_add_u32_e32 v16, v16, v9
	v_add_u32_e32 v16, v16, v10
	v_add_u32_e32 v16, v16, v11
	v_add_u32_e32 v16, v16, v12
	v_add_u32_e32 v16, v16, v13
	v_add_u32_e32 v16, v16, v14
	v_add_u32_e32 v16, v16, v15
	v_cmp_eq_u32_e32 vcc, s1, v16
	s_cbranch_vccnz .LBB0_155
	s_and_b32 s1, s0, 0xff
	s_cmp_eq_u32 s1, 0
	s_mov_b64 s[10:11], -1
	s_sleep 1
	s_cbranch_scc0 .LBB0_160
	v_readlane_b32 s6, v251, 27
	v_readlane_b32 s7, v251, 28
	s_nop 4
	global_load_dword v16, v131, s[6:7] sc1
	s_waitcnt vmcnt(0)
	v_cmp_eq_u32_e32 vcc, 0, v16
	s_cbranch_vccnz .LBB0_162
	s_mov_b64 s[10:11], 0
	s_mov_b64 s[6:7], -1
